# write-through (sc1) on mix-in Proj and attention output stores, whose readers are on other XCDs (on v52)
# speedup vs baseline: 1.0163x; 1.0163x over previous
.LBB0_222:
	s_or_b64 exec, exec, s[6:7]
	s_waitcnt lgkmcnt(0)
	s_barrier
	s_and_saveexec_b64 s[6:7], s[40:41]
	s_cbranch_execz .LBB0_195
	global_load_dwordx4 v[148:151], v[184:185], off
	global_load_dwordx4 v[152:155], v[184:185], off offset:32
	global_load_dwordx4 v[156:159], v[184:185], off offset:64
	global_load_dwordx4 v[162:165], v[184:185], off offset:96
	global_load_dwordx4 v[222:225], v[184:185], off offset:128
	global_load_dwordx4 v[236:239], v[184:185], off offset:160
	global_load_dwordx4 v[240:243], v[184:185], off offset:192
	global_load_dwordx4 v[244:247], v[184:185], off offset:224
	global_load_dwordx4 v[248:251], v[184:185], off offset:256
	global_load_dwordx4 v[230:233], v[184:185], off offset:288
	ds_read2st64_b32 v[78:79], v206 offset1:1
	ds_read2st64_b32 v[82:83], v206 offset0:2 offset1:3
	ds_read2st64_b32 v[96:97], v206 offset0:4 offset1:5
	ds_read2st64_b32 v[86:87], v206 offset0:6 offset1:7
	ds_read2st64_b32 v[100:101], v206 offset0:8 offset1:9
	ds_read2st64_b32 v[118:119], v206 offset0:10 offset1:11
	ds_read2st64_b32 v[120:121], v206 offset0:12 offset1:13
	ds_read2st64_b32 v[122:123], v206 offset0:14 offset1:15
	ds_read2st64_b32 v[124:125], v206 offset0:16 offset1:17
	ds_read2st64_b32 v[126:127], v206 offset0:18 offset1:19
	ds_read2st64_b32 v[128:129], v206 offset0:20 offset1:21
	ds_read2st64_b32 v[130:131], v206 offset0:22 offset1:23
	ds_read2st64_b32 v[132:133], v206 offset0:24 offset1:25
	ds_read2st64_b32 v[134:135], v206 offset0:26 offset1:27
	ds_read2st64_b32 v[114:115], v206 offset0:28 offset1:29
	ds_read2st64_b32 v[136:137], v206 offset0:30 offset1:31
	ds_read2st64_b32 v[110:111], v206 offset0:32 offset1:33
	ds_read2st64_b32 v[116:117], v206 offset0:34 offset1:35
	ds_read2st64_b32 v[106:107], v206 offset0:36 offset1:37
	ds_read2st64_b32 v[112:113], v206 offset0:38 offset1:39
	ds_read2st64_b32 v[102:103], v206 offset0:40 offset1:41
	ds_read2st64_b32 v[108:109], v206 offset0:42 offset1:43
	ds_read2st64_b32 v[98:99], v206 offset0:44 offset1:45
	ds_read2st64_b32 v[104:105], v206 offset0:46 offset1:47
	ds_read2st64_b32 v[90:91], v206 offset0:48 offset1:49
	ds_read2st64_b32 v[94:95], v206 offset0:50 offset1:51
	ds_read2st64_b32 v[76:77], v206 offset0:52 offset1:53
	ds_read2st64_b32 v[84:85], v206 offset0:54 offset1:55
	ds_read2st64_b32 v[74:75], v206 offset0:56 offset1:57
	ds_read2st64_b32 v[80:81], v206 offset0:58 offset1:59
	ds_read2st64_b32 v[64:65], v206 offset0:60 offset1:61
	s_waitcnt lgkmcnt(14)
	v_pk_mul_f32 v[82:83], v[186:187], v[82:83]
	s_lshl_b32 s4, s27, 1
	v_pk_fma_f32 v[82:83], v[50:51], v[70:71], v[82:83] op_sel_hi:[1,0,1] neg_lo:[0,0,1] neg_hi:[0,0,1]
	v_pk_mul_f32 v[50:51], v[186:187], v[78:79]
	s_waitcnt lgkmcnt(0)
	v_pk_mul_f32 v[64:65], v[186:187], v[64:65]
	v_pk_fma_f32 v[92:93], v[48:49], v[70:71], v[50:51] op_sel_hi:[1,0,1] neg_lo:[0,0,1] neg_hi:[0,0,1]
	v_pk_mul_f32 v[48:49], v[186:187], v[86:87]
	v_pk_fma_f32 v[64:65], v[12:13], v[70:71], v[64:65] op_sel_hi:[1,0,1] neg_lo:[0,0,1] neg_hi:[0,0,1]
	v_pk_fma_f32 v[86:87], v[54:55], v[70:71], v[48:49] op_sel_hi:[1,0,1] neg_lo:[0,0,1] neg_hi:[0,0,1]
	v_pk_mul_f32 v[48:49], v[186:187], v[96:97]
	ds_read_b32 v12, v206 offset:15872
	ds_read_b32 v13, v210
	v_pk_fma_f32 v[96:97], v[52:53], v[70:71], v[48:49] op_sel_hi:[1,0,1] neg_lo:[0,0,1] neg_hi:[0,0,1]
	v_pk_mul_f32 v[48:49], v[186:187], v[118:119]
	v_pk_mul_f32 v[140:141], v[92:93], v[92:93]
	v_pk_fma_f32 v[78:79], v[58:59], v[70:71], v[48:49] op_sel_hi:[1,0,1] neg_lo:[0,0,1] neg_hi:[0,0,1]
	v_pk_mul_f32 v[48:49], v[186:187], v[100:101]
	s_waitcnt lgkmcnt(0)
	v_pk_mul_f32 v[12:13], v[186:187], v[12:13]
	v_pk_fma_f32 v[100:101], v[56:57], v[70:71], v[48:49] op_sel_hi:[1,0,1] neg_lo:[0,0,1] neg_hi:[0,0,1]
	v_pk_mul_f32 v[48:49], v[186:187], v[122:123]
	v_pk_fma_f32 v[68:69], v[14:15], v[70:71], v[12:13] op_sel_hi:[1,0,1] neg_lo:[0,0,1] neg_hi:[0,0,1]
	v_pk_fma_f32 v[56:57], v[62:63], v[70:71], v[48:49] op_sel_hi:[1,0,1] neg_lo:[0,0,1] neg_hi:[0,0,1]
	v_pk_mul_f32 v[48:49], v[186:187], v[120:121]
	v_lshl_add_u64 v[12:13], s[20:21], 0, v[160:161]
	v_pk_fma_f32 v[60:61], v[60:61], v[70:71], v[48:49] op_sel_hi:[1,0,1] neg_lo:[0,0,1] neg_hi:[0,0,1]
	v_pk_mul_f32 v[48:49], v[186:187], v[126:127]
	v_lshl_add_u64 v[12:13], v[12:13], 0, s[4:5]
	v_pk_fma_f32 v[52:53], v[34:35], v[70:71], v[48:49] op_sel_hi:[1,0,1] neg_lo:[0,0,1] neg_hi:[0,0,1]
	v_pk_mul_f32 v[34:35], v[186:187], v[124:125]
	v_lshlrev_b32_e32 v160, 1, v180
	v_pk_fma_f32 v[58:59], v[32:33], v[70:71], v[34:35] op_sel_hi:[1,0,1] neg_lo:[0,0,1] neg_hi:[0,0,1]
	v_pk_mul_f32 v[32:33], v[186:187], v[130:131]
	v_lshl_add_u64 v[66:67], v[12:13], 0, v[160:161]
	v_pk_fma_f32 v[48:49], v[38:39], v[70:71], v[32:33] op_sel_hi:[1,0,1] neg_lo:[0,0,1] neg_hi:[0,0,1]
	v_pk_mul_f32 v[32:33], v[186:187], v[128:129]
	v_pk_fma_f32 v[54:55], v[36:37], v[70:71], v[32:33] op_sel_hi:[1,0,1] neg_lo:[0,0,1] neg_hi:[0,0,1]
	v_pk_mul_f32 v[32:33], v[186:187], v[134:135]
	v_pk_mul_f32 v[138:139], v[82:83], v[82:83]
	v_pk_fma_f32 v[42:43], v[42:43], v[70:71], v[32:33] op_sel_hi:[1,0,1] neg_lo:[0,0,1] neg_hi:[0,0,1]
	v_pk_mul_f32 v[32:33], v[186:187], v[132:133]
	v_pk_mul_f32 v[144:145], v[96:97], v[96:97]
	v_pk_fma_f32 v[50:51], v[40:41], v[70:71], v[32:33] op_sel_hi:[1,0,1] neg_lo:[0,0,1] neg_hi:[0,0,1]
	v_pk_mul_f32 v[32:33], v[186:187], v[136:137]
	v_pk_mul_f32 v[142:143], v[86:87], v[86:87]
	v_pk_fma_f32 v[38:39], v[46:47], v[70:71], v[32:33] op_sel_hi:[1,0,1] neg_lo:[0,0,1] neg_hi:[0,0,1]
	v_pk_mul_f32 v[32:33], v[186:187], v[114:115]
	v_pk_mul_f32 v[146:147], v[100:101], v[100:101]
	v_pk_fma_f32 v[44:45], v[44:45], v[70:71], v[32:33] op_sel_hi:[1,0,1] neg_lo:[0,0,1] neg_hi:[0,0,1]
	v_pk_mul_f32 v[32:33], v[186:187], v[116:117]
	v_pk_mul_f32 v[118:119], v[78:79], v[78:79]
	v_pk_fma_f32 v[34:35], v[18:19], v[70:71], v[32:33] op_sel_hi:[1,0,1] neg_lo:[0,0,1] neg_hi:[0,0,1]
	v_pk_mul_f32 v[18:19], v[186:187], v[110:111]
	v_pk_mul_f32 v[120:121], v[60:61], v[60:61]
	v_pk_fma_f32 v[40:41], v[16:17], v[70:71], v[18:19] op_sel_hi:[1,0,1] neg_lo:[0,0,1] neg_hi:[0,0,1]
	v_pk_mul_f32 v[16:17], v[186:187], v[112:113]
	v_pk_mul_f32 v[62:63], v[56:57], v[56:57]
	v_pk_fma_f32 v[32:33], v[22:23], v[70:71], v[16:17] op_sel_hi:[1,0,1] neg_lo:[0,0,1] neg_hi:[0,0,1]
	v_pk_mul_f32 v[16:17], v[186:187], v[106:107]
	v_pk_mul_f32 v[124:125], v[58:59], v[58:59]
	v_pk_fma_f32 v[36:37], v[20:21], v[70:71], v[16:17] op_sel_hi:[1,0,1] neg_lo:[0,0,1] neg_hi:[0,0,1]
	v_pk_mul_f32 v[16:17], v[186:187], v[108:109]
	v_pk_mul_f32 v[122:123], v[52:53], v[52:53]
	v_pk_fma_f32 v[22:23], v[26:27], v[70:71], v[16:17] op_sel_hi:[1,0,1] neg_lo:[0,0,1] neg_hi:[0,0,1]
	v_pk_mul_f32 v[16:17], v[186:187], v[102:103]
	v_pk_mul_f32 v[128:129], v[54:55], v[54:55]
	v_pk_fma_f32 v[26:27], v[24:25], v[70:71], v[16:17] op_sel_hi:[1,0,1] neg_lo:[0,0,1] neg_hi:[0,0,1]
	v_pk_mul_f32 v[16:17], v[186:187], v[104:105]
	v_pk_mul_f32 v[126:127], v[48:49], v[48:49]
	v_pk_fma_f32 v[18:19], v[30:31], v[70:71], v[16:17] op_sel_hi:[1,0,1] neg_lo:[0,0,1] neg_hi:[0,0,1]
	v_pk_mul_f32 v[16:17], v[186:187], v[98:99]
	v_pk_mul_f32 v[132:133], v[50:51], v[50:51]
	v_pk_fma_f32 v[24:25], v[28:29], v[70:71], v[16:17] op_sel_hi:[1,0,1] neg_lo:[0,0,1] neg_hi:[0,0,1]
	v_pk_mul_f32 v[16:17], v[186:187], v[94:95]
	v_pk_mul_f32 v[130:131], v[42:43], v[42:43]
	v_pk_fma_f32 v[16:17], v[2:3], v[70:71], v[16:17] op_sel_hi:[1,0,1] neg_lo:[0,0,1] neg_hi:[0,0,1]
	v_pk_mul_f32 v[2:3], v[186:187], v[90:91]
	v_pk_mul_f32 v[114:115], v[44:45], v[44:45]
	v_pk_fma_f32 v[20:21], v[0:1], v[70:71], v[2:3] op_sel_hi:[1,0,1] neg_lo:[0,0,1] neg_hi:[0,0,1]
	v_pk_mul_f32 v[0:1], v[186:187], v[84:85]
	v_pk_mul_f32 v[46:47], v[38:39], v[38:39]
	v_pk_fma_f32 v[2:3], v[6:7], v[70:71], v[0:1] op_sel_hi:[1,0,1] neg_lo:[0,0,1] neg_hi:[0,0,1]
	v_pk_mul_f32 v[0:1], v[186:187], v[76:77]
	v_pk_mul_f32 v[110:111], v[40:41], v[40:41]
	v_pk_fma_f32 v[6:7], v[4:5], v[70:71], v[0:1] op_sel_hi:[1,0,1] neg_lo:[0,0,1] neg_hi:[0,0,1]
	v_pk_mul_f32 v[0:1], v[186:187], v[80:81]
	v_pk_mul_f32 v[4:5], v[186:187], v[74:75]
	v_pk_fma_f32 v[0:1], v[10:11], v[70:71], v[0:1] op_sel_hi:[1,0,1] neg_lo:[0,0,1] neg_hi:[0,0,1]
	v_pk_fma_f32 v[4:5], v[8:9], v[70:71], v[4:5] op_sel_hi:[1,0,1] neg_lo:[0,0,1] neg_hi:[0,0,1]
	v_add_f32_e32 v70, v140, v141
	v_add_f32_e32 v70, v70, v138
	v_add_f32_e32 v70, v70, v139
	v_add_f32_e32 v70, v70, v144
	v_add_f32_e32 v70, v70, v145
	v_add_f32_e32 v70, v70, v142
	v_add_f32_e32 v70, v70, v143
	v_add_f32_e32 v70, v70, v146
	v_add_f32_e32 v70, v70, v147
	v_add_f32_e32 v70, v70, v118
	v_add_f32_e32 v70, v70, v119
	v_add_f32_e32 v70, v70, v120
	v_add_f32_e32 v70, v70, v121
	v_add_f32_e32 v62, v70, v62
	v_add_f32_e32 v62, v62, v63
	v_add_f32_e32 v62, v62, v124
	v_add_f32_e32 v62, v62, v125
	v_add_f32_e32 v62, v62, v122
	v_add_f32_e32 v62, v62, v123
	v_add_f32_e32 v62, v62, v128
	v_add_f32_e32 v62, v62, v129
	v_add_f32_e32 v62, v62, v126
	v_add_f32_e32 v62, v62, v127
	v_add_f32_e32 v62, v62, v132
	v_add_f32_e32 v62, v62, v133
	v_add_f32_e32 v62, v62, v130
	v_add_f32_e32 v62, v62, v131
	v_add_f32_e32 v62, v62, v114
	v_add_f32_e32 v62, v62, v115
	v_add_f32_e32 v46, v62, v46
	v_add_f32_e32 v46, v46, v47
	v_add_f32_e32 v46, v46, v110
	v_pk_mul_f32 v[116:117], v[34:35], v[34:35]
	v_add_f32_e32 v46, v46, v111
	v_add_f32_e32 v46, v46, v116
	v_pk_mul_f32 v[106:107], v[36:37], v[36:37]
	v_add_f32_e32 v46, v46, v117
	v_add_f32_e32 v46, v46, v106
	v_pk_mul_f32 v[112:113], v[32:33], v[32:33]
	v_add_f32_e32 v46, v46, v107
	v_add_f32_e32 v46, v46, v112
	v_pk_mul_f32 v[102:103], v[26:27], v[26:27]
	v_add_f32_e32 v46, v46, v113
	v_add_f32_e32 v46, v46, v102
	v_pk_mul_f32 v[108:109], v[22:23], v[22:23]
	v_add_f32_e32 v46, v46, v103
	v_add_f32_e32 v46, v46, v108
	v_pk_mul_f32 v[28:29], v[24:25], v[24:25]
	v_add_f32_e32 v46, v46, v109
	v_add_f32_e32 v28, v46, v28
	v_pk_mul_f32 v[30:31], v[18:19], v[18:19]
	v_add_f32_e32 v28, v28, v29
	v_add_f32_e32 v28, v28, v30
	v_pk_mul_f32 v[90:91], v[20:21], v[20:21]
	v_add_f32_e32 v28, v28, v31
	v_add_f32_e32 v28, v28, v90
	v_pk_mul_f32 v[94:95], v[16:17], v[16:17]
	v_add_f32_e32 v28, v28, v91
	v_add_f32_e32 v28, v28, v94
	v_pk_mul_f32 v[76:77], v[6:7], v[6:7]
	v_add_f32_e32 v28, v28, v95
	v_add_f32_e32 v28, v28, v76
	v_pk_mul_f32 v[84:85], v[2:3], v[2:3]
	v_add_f32_e32 v28, v28, v77
	v_add_f32_e32 v28, v28, v84
	v_pk_mul_f32 v[8:9], v[4:5], v[4:5]
	v_add_f32_e32 v28, v28, v85
	v_add_f32_e32 v8, v28, v8
	v_pk_mul_f32 v[10:11], v[0:1], v[0:1]
	v_add_f32_e32 v8, v8, v9
	v_add_f32_e32 v8, v8, v10
	v_pk_mul_f32 v[72:73], v[64:65], v[64:65]
	v_add_f32_e32 v8, v8, v11
	v_add_f32_e32 v8, v8, v72
	v_pk_mul_f32 v[88:89], v[68:69], v[68:69]
	v_add_f32_e32 v8, v8, v73
	v_add_f32_e32 v8, v8, v88
	v_add_f32_e32 v8, v8, v89
	global_load_dwordx4 v[102:105], v[184:185], off offset:320
	global_load_dwordx4 v[106:109], v[184:185], off offset:352
	global_load_dwordx4 v[110:113], v[184:185], off offset:384
	global_load_dwordx4 v[114:117], v[184:185], off offset:416
	global_load_dwordx4 v[118:121], v[184:185], off offset:448
	global_load_dwordx4 v[122:125], v[184:185], off offset:480
	ds_bpermute_b32 v9, v173, v8
	s_waitcnt lgkmcnt(0)
	v_add_f32_e32 v8, v8, v9
	v_fmamk_f32 v8, v8, 0x3c000000, v216
	v_cmp_gt_f32_e32 vcc, s29, v8
	v_mul_f32_e32 v9, 0x4b800000, v8
	s_nop 0
	v_cndmask_b32_e32 v8, v8, v9, vcc
	v_rsq_f32_e32 v8, v8
	s_nop 0
	v_mul_f32_e32 v9, 0x45800000, v8
	v_cndmask_b32_e32 v8, v8, v9, vcc
	v_mul_f32_e32 v8, v171, v8
	v_pk_mul_f32 v[10:11], v[92:93], v[8:9] op_sel_hi:[1,0]
	v_pk_mul_f32 v[12:13], v[82:83], v[8:9] op_sel_hi:[1,0]
	s_waitcnt vmcnt(15)
	v_pk_mul_f32 v[10:11], v[148:149], v[10:11]
	v_pk_mul_f32 v[12:13], v[150:151], v[12:13]
	v_cvt_pk_bf16_f32 v10, v10, v11
	v_cvt_pk_bf16_f32 v11, v12, v13
	global_store_dwordx2 v[66:67], v[10:11], off sc1
	v_pk_mul_f32 v[70:71], v[96:97], v[8:9] op_sel_hi:[1,0]
	v_pk_mul_f32 v[72:73], v[86:87], v[8:9] op_sel_hi:[1,0]
	s_waitcnt vmcnt(15)
	v_pk_mul_f32 v[70:71], v[152:153], v[70:71]
	v_pk_mul_f32 v[72:73], v[154:155], v[72:73]
	v_cvt_pk_bf16_f32 v70, v70, v71
	v_cvt_pk_bf16_f32 v71, v72, v73
	global_store_dwordx2 v[66:67], v[70:71], off offset:16 sc1
	v_pk_mul_f32 v[10:11], v[100:101], v[8:9] op_sel_hi:[1,0]
	v_pk_mul_f32 v[12:13], v[78:79], v[8:9] op_sel_hi:[1,0]
	s_waitcnt vmcnt(15)
	v_pk_mul_f32 v[10:11], v[156:157], v[10:11]
	v_pk_mul_f32 v[12:13], v[158:159], v[12:13]
	v_cvt_pk_bf16_f32 v10, v10, v11
	v_cvt_pk_bf16_f32 v11, v12, v13
	global_store_dwordx2 v[66:67], v[10:11], off offset:32 sc1
	v_pk_mul_f32 v[70:71], v[60:61], v[8:9] op_sel_hi:[1,0]
	v_pk_mul_f32 v[72:73], v[56:57], v[8:9] op_sel_hi:[1,0]
	s_waitcnt vmcnt(15)
	v_pk_mul_f32 v[70:71], v[162:163], v[70:71]
	v_pk_mul_f32 v[72:73], v[164:165], v[72:73]
	v_cvt_pk_bf16_f32 v70, v70, v71
	v_cvt_pk_bf16_f32 v71, v72, v73
	global_store_dwordx2 v[66:67], v[70:71], off offset:48 sc1
	v_pk_mul_f32 v[10:11], v[58:59], v[8:9] op_sel_hi:[1,0]
	v_pk_mul_f32 v[12:13], v[52:53], v[8:9] op_sel_hi:[1,0]
	s_waitcnt vmcnt(15)
	v_pk_mul_f32 v[10:11], v[222:223], v[10:11]
	v_pk_mul_f32 v[12:13], v[224:225], v[12:13]
	v_cvt_pk_bf16_f32 v10, v10, v11
	v_cvt_pk_bf16_f32 v11, v12, v13
	global_store_dwordx2 v[66:67], v[10:11], off offset:64 sc1
	v_pk_mul_f32 v[70:71], v[54:55], v[8:9] op_sel_hi:[1,0]
	v_pk_mul_f32 v[72:73], v[48:49], v[8:9] op_sel_hi:[1,0]
	s_waitcnt vmcnt(15)
	v_pk_mul_f32 v[70:71], v[236:237], v[70:71]
	v_pk_mul_f32 v[72:73], v[238:239], v[72:73]
	v_cvt_pk_bf16_f32 v70, v70, v71
	v_cvt_pk_bf16_f32 v71, v72, v73
	global_store_dwordx2 v[66:67], v[70:71], off offset:80 sc1
	v_pk_mul_f32 v[10:11], v[50:51], v[8:9] op_sel_hi:[1,0]
	v_pk_mul_f32 v[12:13], v[42:43], v[8:9] op_sel_hi:[1,0]
	s_waitcnt vmcnt(15)
	v_pk_mul_f32 v[10:11], v[240:241], v[10:11]
	v_pk_mul_f32 v[12:13], v[242:243], v[12:13]
	v_cvt_pk_bf16_f32 v10, v10, v11
	v_cvt_pk_bf16_f32 v11, v12, v13
	global_store_dwordx2 v[66:67], v[10:11], off offset:96 sc1
	v_pk_mul_f32 v[70:71], v[44:45], v[8:9] op_sel_hi:[1,0]
	v_pk_mul_f32 v[72:73], v[38:39], v[8:9] op_sel_hi:[1,0]
	s_waitcnt vmcnt(15)
	v_pk_mul_f32 v[70:71], v[244:245], v[70:71]
	v_pk_mul_f32 v[72:73], v[246:247], v[72:73]
	v_cvt_pk_bf16_f32 v70, v70, v71
	v_cvt_pk_bf16_f32 v71, v72, v73
	global_store_dwordx2 v[66:67], v[70:71], off offset:112 sc1
	v_pk_mul_f32 v[10:11], v[40:41], v[8:9] op_sel_hi:[1,0]
	v_pk_mul_f32 v[12:13], v[34:35], v[8:9] op_sel_hi:[1,0]
	s_waitcnt vmcnt(15)
	v_pk_mul_f32 v[10:11], v[248:249], v[10:11]
	v_pk_mul_f32 v[12:13], v[250:251], v[12:13]
	v_cvt_pk_bf16_f32 v10, v10, v11
	v_cvt_pk_bf16_f32 v11, v12, v13
	global_store_dwordx2 v[66:67], v[10:11], off offset:128 sc1
	v_pk_mul_f32 v[70:71], v[36:37], v[8:9] op_sel_hi:[1,0]
	v_pk_mul_f32 v[72:73], v[32:33], v[8:9] op_sel_hi:[1,0]
	s_waitcnt vmcnt(15)
	v_pk_mul_f32 v[70:71], v[230:231], v[70:71]
	v_pk_mul_f32 v[72:73], v[232:233], v[72:73]
	v_cvt_pk_bf16_f32 v70, v70, v71
	v_cvt_pk_bf16_f32 v71, v72, v73
	global_store_dwordx2 v[66:67], v[70:71], off offset:144 sc1
	v_pk_mul_f32 v[10:11], v[26:27], v[8:9] op_sel_hi:[1,0]
	v_pk_mul_f32 v[12:13], v[22:23], v[8:9] op_sel_hi:[1,0]
	s_waitcnt vmcnt(15)
	v_pk_mul_f32 v[10:11], v[102:103], v[10:11]
	v_pk_mul_f32 v[12:13], v[104:105], v[12:13]
	v_cvt_pk_bf16_f32 v10, v10, v11
	v_cvt_pk_bf16_f32 v11, v12, v13
	global_store_dwordx2 v[66:67], v[10:11], off offset:160 sc1
	v_pk_mul_f32 v[70:71], v[24:25], v[8:9] op_sel_hi:[1,0]
	v_pk_mul_f32 v[72:73], v[18:19], v[8:9] op_sel_hi:[1,0]
	s_waitcnt vmcnt(15)
	v_pk_mul_f32 v[70:71], v[106:107], v[70:71]
	v_pk_mul_f32 v[72:73], v[108:109], v[72:73]
	v_cvt_pk_bf16_f32 v70, v70, v71
	v_cvt_pk_bf16_f32 v71, v72, v73
	global_store_dwordx2 v[66:67], v[70:71], off offset:176 sc1
	v_pk_mul_f32 v[10:11], v[20:21], v[8:9] op_sel_hi:[1,0]
	v_pk_mul_f32 v[12:13], v[16:17], v[8:9] op_sel_hi:[1,0]
	s_waitcnt vmcnt(15)
	v_pk_mul_f32 v[10:11], v[110:111], v[10:11]
	v_pk_mul_f32 v[12:13], v[112:113], v[12:13]
	v_cvt_pk_bf16_f32 v10, v10, v11
	v_cvt_pk_bf16_f32 v11, v12, v13
	global_store_dwordx2 v[66:67], v[10:11], off offset:192 sc1
	v_pk_mul_f32 v[70:71], v[6:7], v[8:9] op_sel_hi:[1,0]
	v_pk_mul_f32 v[72:73], v[2:3], v[8:9] op_sel_hi:[1,0]
	s_waitcnt vmcnt(15)
	v_pk_mul_f32 v[70:71], v[114:115], v[70:71]
	v_pk_mul_f32 v[72:73], v[116:117], v[72:73]
	v_cvt_pk_bf16_f32 v70, v70, v71
	v_cvt_pk_bf16_f32 v71, v72, v73
	global_store_dwordx2 v[66:67], v[70:71], off offset:208 sc1
	v_pk_mul_f32 v[10:11], v[4:5], v[8:9] op_sel_hi:[1,0]
	v_pk_mul_f32 v[12:13], v[0:1], v[8:9] op_sel_hi:[1,0]
	s_waitcnt vmcnt(15)
	v_pk_mul_f32 v[10:11], v[118:119], v[10:11]
	v_pk_mul_f32 v[12:13], v[120:121], v[12:13]
	v_cvt_pk_bf16_f32 v10, v10, v11
	v_cvt_pk_bf16_f32 v11, v12, v13
	global_store_dwordx2 v[66:67], v[10:11], off offset:224 sc1
	v_pk_mul_f32 v[70:71], v[64:65], v[8:9] op_sel_hi:[1,0]
	v_pk_mul_f32 v[72:73], v[68:69], v[8:9] op_sel_hi:[1,0]
	s_waitcnt vmcnt(15)
	v_pk_mul_f32 v[70:71], v[122:123], v[70:71]
	v_pk_mul_f32 v[72:73], v[124:125], v[72:73]
	v_cvt_pk_bf16_f32 v70, v70, v71
	v_cvt_pk_bf16_f32 v71, v72, v73
	global_store_dwordx2 v[66:67], v[70:71], off offset:240 sc1
	s_branch .LBB0_195

.LBB0_264:
	v_cvt_pk_bf16_f32 v116, v116, v117
	v_cvt_pk_bf16_f32 v117, v118, v119
	v_cvt_pk_bf16_f32 v119, v114, v115
	v_or_b32_e32 v114, 16, v148
	v_ashrrev_i32_e32 v115, 31, v114
	v_cvt_pk_bf16_f32 v118, v112, v113
	v_lshlrev_b64 v[112:113], 6, v[114:115]
	global_store_dwordx4 v[120:121], v[116:119], off offset:256 sc1
	s_and_b64 vcc, exec, s[40:41]
	s_nop 0
	v_lshl_add_u64 v[116:117], v[142:143], 0, v[112:113]
	v_mov_b32_e32 v116, v196
	v_mov_b32_e32 v117, v197
	v_mov_b32_e32 v118, v198
	v_mov_b32_e32 v119, v199
	v_mov_b32_e32 v120, v117
	v_mov_b32_e32 v121, v118
	v_mov_b32_e32 v117, v119
	v_pk_add_f32 v[116:117], v[120:121], v[116:117]
	s_nop 0
	v_add_f32_e32 v116, v116, v117
	ds_bpermute_b32 v117, v169, v116
	s_waitcnt lgkmcnt(0)
	v_add_f32_e32 v116, v116, v117
	ds_bpermute_b32 v117, v172, v116
	s_waitcnt lgkmcnt(0)
	v_add_f32_e32 v116, v116, v117
	v_fmamk_f32 v116, v116, 0x3a800000, v216
	v_mul_f32_e32 v117, 0x4b800000, v116
	v_cmp_gt_f32_e64 s[42:43], s29, v116
	s_nop 1
	v_cndmask_b32_e64 v116, v116, v117, s[42:43]
	v_rsq_f32_e32 v116, v116
	s_nop 0
	v_mul_f32_e32 v117, 0x45800000, v116
	v_cndmask_b32_e64 v116, v116, v117, s[42:43]
	v_mul_f32_e32 v116, v174, v116
	v_pk_mul_f32 v[110:111], v[110:111], v[116:117] op_sel_hi:[1,0]
	v_pk_mul_f32 v[108:109], v[108:109], v[116:117] op_sel_hi:[1,0]
	v_pk_mul_f32 v[106:107], v[106:107], v[116:117] op_sel_hi:[1,0]
	v_pk_mul_f32 v[104:105], v[104:105], v[116:117] op_sel_hi:[1,0]
	s_cbranch_vccnz .LBB0_268
	ds_bpermute_b32 v124, v169, v108
	ds_bpermute_b32 v120, v169, v104
	ds_bpermute_b32 v125, v169, v109
	ds_bpermute_b32 v121, v169, v105
	ds_bpermute_b32 v122, v169, v110
	ds_bpermute_b32 v118, v169, v106
	ds_bpermute_b32 v123, v169, v111
	ds_bpermute_b32 v119, v169, v107
	s_and_saveexec_b64 s[42:43], s[36:37]
	s_cbranch_execz .LBB0_267
	v_lshl_add_u64 v[126:127], s[20:21], 0, v[112:113]
	global_load_dwordx4 v[150:153], v[126:127], off
	global_load_dwordx4 v[154:157], v[126:127], off offset:32
	global_load_dwordx4 v[176:179], v[126:127], off offset:16
	global_load_dwordx4 v[180:183], v[126:127], off offset:48
	s_waitcnt vmcnt(3)
	v_pk_mul_f32 v[110:111], v[110:111], v[152:153]
	v_pk_mul_f32 v[108:109], v[108:109], v[150:151]
	s_waitcnt vmcnt(2) lgkmcnt(5)
	v_pk_mul_f32 v[124:125], v[154:155], v[124:125]
	s_waitcnt lgkmcnt(1)
	v_pk_mul_f32 v[122:123], v[156:157], v[122:123]
	s_waitcnt vmcnt(1)
	v_pk_mul_f32 v[106:107], v[106:107], v[178:179]
	v_pk_mul_f32 v[104:105], v[104:105], v[176:177]
	s_waitcnt vmcnt(0)
	v_pk_mul_f32 v[120:121], v[180:181], v[120:121]
	s_waitcnt lgkmcnt(0)
	v_pk_mul_f32 v[118:119], v[182:183], v[118:119]
	v_pk_fma_f32 v[110:111], v[140:141], v[122:123], v[110:111]
	v_pk_fma_f32 v[108:109], v[138:139], v[124:125], v[108:109]
	v_pk_fma_f32 v[106:107], v[140:141], v[118:119], v[106:107]
	v_pk_fma_f32 v[104:105], v[138:139], v[120:121], v[104:105]

.LBB0_272:
	v_cvt_pk_bf16_f32 v100, v100, v101
	v_cvt_pk_bf16_f32 v101, v102, v103
	v_cvt_pk_bf16_f32 v103, v98, v99
	v_or_b32_e32 v98, 32, v148
	v_ashrrev_i32_e32 v99, 31, v98
	v_cvt_pk_bf16_f32 v102, v96, v97
	v_lshlrev_b64 v[96:97], 6, v[98:99]
	global_store_dwordx4 v[104:105], v[100:103], off offset:256 sc1
	s_and_b64 vcc, exec, s[40:41]
	s_nop 0
	v_lshl_add_u64 v[100:101], v[142:143], 0, v[96:97]
	v_mov_b32_e32 v100, v200
	v_mov_b32_e32 v101, v201
	v_mov_b32_e32 v102, v202
	v_mov_b32_e32 v103, v203
	v_mov_b32_e32 v104, v101
	v_mov_b32_e32 v105, v102
	v_mov_b32_e32 v101, v103
	v_pk_add_f32 v[100:101], v[104:105], v[100:101]
	s_nop 0
	v_add_f32_e32 v100, v100, v101
	ds_bpermute_b32 v101, v169, v100
	s_waitcnt lgkmcnt(0)
	v_add_f32_e32 v100, v100, v101
	ds_bpermute_b32 v101, v172, v100
	s_waitcnt lgkmcnt(0)
	v_add_f32_e32 v100, v100, v101
	v_fmamk_f32 v100, v100, 0x3a800000, v216
	v_mul_f32_e32 v101, 0x4b800000, v100
	v_cmp_gt_f32_e64 s[42:43], s29, v100
	s_nop 1
	v_cndmask_b32_e64 v100, v100, v101, s[42:43]
	v_rsq_f32_e32 v100, v100
	s_nop 0
	v_mul_f32_e32 v101, 0x45800000, v100
	v_cndmask_b32_e64 v100, v100, v101, s[42:43]
	v_mul_f32_e32 v100, v174, v100
	v_pk_mul_f32 v[94:95], v[94:95], v[100:101] op_sel_hi:[1,0]
	v_pk_mul_f32 v[92:93], v[92:93], v[100:101] op_sel_hi:[1,0]
	v_pk_mul_f32 v[90:91], v[90:91], v[100:101] op_sel_hi:[1,0]
	v_pk_mul_f32 v[88:89], v[88:89], v[100:101] op_sel_hi:[1,0]
	s_cbranch_vccnz .LBB0_276
	ds_bpermute_b32 v108, v169, v92
	ds_bpermute_b32 v104, v169, v88
	ds_bpermute_b32 v109, v169, v93
	ds_bpermute_b32 v105, v169, v89
	ds_bpermute_b32 v106, v169, v94
	ds_bpermute_b32 v102, v169, v90
	ds_bpermute_b32 v107, v169, v95
	ds_bpermute_b32 v103, v169, v91
	s_and_saveexec_b64 s[42:43], s[36:37]
	s_cbranch_execz .LBB0_275
	v_lshl_add_u64 v[122:123], s[20:21], 0, v[96:97]
	global_load_dwordx4 v[110:113], v[122:123], off
	global_load_dwordx4 v[114:117], v[122:123], off offset:32
	global_load_dwordx4 v[118:121], v[122:123], off offset:16
	s_nop 0
	global_load_dwordx4 v[122:125], v[122:123], off offset:48
	s_waitcnt vmcnt(3)
	v_pk_mul_f32 v[94:95], v[94:95], v[112:113]
	v_pk_mul_f32 v[92:93], v[92:93], v[110:111]
	s_waitcnt vmcnt(2) lgkmcnt(5)
	v_pk_mul_f32 v[108:109], v[114:115], v[108:109]
	s_waitcnt lgkmcnt(1)
	v_pk_mul_f32 v[106:107], v[116:117], v[106:107]
	s_waitcnt vmcnt(1)
	v_pk_mul_f32 v[90:91], v[90:91], v[120:121]
	v_pk_mul_f32 v[88:89], v[88:89], v[118:119]
	s_waitcnt vmcnt(0)
	v_pk_mul_f32 v[104:105], v[122:123], v[104:105]
	s_waitcnt lgkmcnt(0)
	v_pk_mul_f32 v[102:103], v[124:125], v[102:103]
	v_pk_fma_f32 v[94:95], v[140:141], v[106:107], v[94:95]
	v_pk_fma_f32 v[92:93], v[138:139], v[108:109], v[92:93]
	v_pk_fma_f32 v[90:91], v[140:141], v[102:103], v[90:91]
	v_pk_fma_f32 v[88:89], v[138:139], v[104:105], v[88:89]

.LBB0_280:
	v_cvt_pk_bf16_f32 v84, v84, v85
	v_cvt_pk_bf16_f32 v85, v86, v87
	v_cvt_pk_bf16_f32 v87, v82, v83
	v_or_b32_e32 v82, 48, v148
	v_ashrrev_i32_e32 v83, 31, v82
	v_cvt_pk_bf16_f32 v86, v80, v81
	v_lshlrev_b64 v[80:81], 6, v[82:83]
	global_store_dwordx4 v[88:89], v[84:87], off offset:256 sc1
	s_and_b64 vcc, exec, s[40:41]
	s_nop 0
	v_lshl_add_u64 v[84:85], v[142:143], 0, v[80:81]
	v_mov_b32_e32 v84, v204
	v_mov_b32_e32 v85, v205
	v_mov_b32_e32 v86, v206
	v_mov_b32_e32 v87, v207
	v_mov_b32_e32 v88, v85
	v_mov_b32_e32 v89, v86
	v_mov_b32_e32 v85, v87
	v_pk_add_f32 v[84:85], v[88:89], v[84:85]
	s_nop 0
	v_add_f32_e32 v84, v84, v85
	ds_bpermute_b32 v85, v169, v84
	s_waitcnt lgkmcnt(0)
	v_add_f32_e32 v84, v84, v85
	ds_bpermute_b32 v85, v172, v84
	s_waitcnt lgkmcnt(0)
	v_add_f32_e32 v84, v84, v85
	v_fmamk_f32 v84, v84, 0x3a800000, v216
	v_mul_f32_e32 v85, 0x4b800000, v84
	v_cmp_gt_f32_e64 s[42:43], s29, v84
	s_nop 1
	v_cndmask_b32_e64 v84, v84, v85, s[42:43]
	v_rsq_f32_e32 v84, v84
	s_nop 0
	v_mul_f32_e32 v85, 0x45800000, v84
	v_cndmask_b32_e64 v84, v84, v85, s[42:43]
	v_mul_f32_e32 v84, v174, v84
	v_pk_mul_f32 v[78:79], v[78:79], v[84:85] op_sel_hi:[1,0]
	v_pk_mul_f32 v[76:77], v[76:77], v[84:85] op_sel_hi:[1,0]
	v_pk_mul_f32 v[74:75], v[74:75], v[84:85] op_sel_hi:[1,0]
	v_pk_mul_f32 v[72:73], v[72:73], v[84:85] op_sel_hi:[1,0]
	s_cbranch_vccnz .LBB0_284
	ds_bpermute_b32 v92, v169, v76
	ds_bpermute_b32 v88, v169, v72
	ds_bpermute_b32 v93, v169, v77
	ds_bpermute_b32 v89, v169, v73
	ds_bpermute_b32 v90, v169, v78
	ds_bpermute_b32 v86, v169, v74
	ds_bpermute_b32 v91, v169, v79
	ds_bpermute_b32 v87, v169, v75
	s_and_saveexec_b64 s[42:43], s[36:37]
	s_cbranch_execz .LBB0_283
	v_lshl_add_u64 v[106:107], s[20:21], 0, v[80:81]
	global_load_dwordx4 v[94:97], v[106:107], off
	global_load_dwordx4 v[98:101], v[106:107], off offset:32
	global_load_dwordx4 v[102:105], v[106:107], off offset:16
	s_nop 0
	global_load_dwordx4 v[106:109], v[106:107], off offset:48
	s_waitcnt vmcnt(3)
	v_pk_mul_f32 v[78:79], v[78:79], v[96:97]
	v_pk_mul_f32 v[76:77], v[76:77], v[94:95]
	s_waitcnt vmcnt(2) lgkmcnt(5)
	v_pk_mul_f32 v[92:93], v[98:99], v[92:93]
	s_waitcnt lgkmcnt(1)
	v_pk_mul_f32 v[90:91], v[100:101], v[90:91]
	s_waitcnt vmcnt(1)
	v_pk_mul_f32 v[74:75], v[74:75], v[104:105]
	v_pk_mul_f32 v[72:73], v[72:73], v[102:103]
	s_waitcnt vmcnt(0)
	v_pk_mul_f32 v[88:89], v[106:107], v[88:89]
	s_waitcnt lgkmcnt(0)
	v_pk_mul_f32 v[86:87], v[108:109], v[86:87]
	v_pk_fma_f32 v[78:79], v[140:141], v[90:91], v[78:79]
	v_pk_fma_f32 v[76:77], v[138:139], v[92:93], v[76:77]
	v_pk_fma_f32 v[74:75], v[140:141], v[86:87], v[74:75]
	v_pk_fma_f32 v[72:73], v[138:139], v[88:89], v[72:73]

.LBB0_288:
	v_cvt_pk_bf16_f32 v68, v68, v69
	v_cvt_pk_bf16_f32 v69, v70, v71
	v_cvt_pk_bf16_f32 v71, v66, v67
	v_add_u32_e32 v66, 0x80, v148
	v_ashrrev_i32_e32 v67, 31, v66
	v_cvt_pk_bf16_f32 v70, v64, v65
	v_lshlrev_b64 v[64:65], 6, v[66:67]
	global_store_dwordx4 v[72:73], v[68:71], off offset:256 sc1
	s_and_b64 vcc, exec, s[40:41]
	s_nop 0
	v_lshl_add_u64 v[68:69], v[142:143], 0, v[64:65]
	v_mov_b32_e32 v68, v234
	v_mov_b32_e32 v69, v235
	v_mov_b32_e32 v70, v236
	v_mov_b32_e32 v71, v237
	v_mov_b32_e32 v72, v69
	v_mov_b32_e32 v73, v70
	v_mov_b32_e32 v69, v71
	v_pk_add_f32 v[68:69], v[72:73], v[68:69]
	s_nop 0
	v_add_f32_e32 v68, v68, v69
	ds_bpermute_b32 v69, v169, v68
	s_waitcnt lgkmcnt(0)
	v_add_f32_e32 v68, v68, v69
	ds_bpermute_b32 v69, v172, v68
	s_waitcnt lgkmcnt(0)
	v_add_f32_e32 v68, v68, v69
	v_fmamk_f32 v68, v68, 0x3a800000, v216
	v_mul_f32_e32 v69, 0x4b800000, v68
	v_cmp_gt_f32_e64 s[42:43], s29, v68
	s_nop 1
	v_cndmask_b32_e64 v68, v68, v69, s[42:43]
	v_rsq_f32_e32 v68, v68
	s_nop 0
	v_mul_f32_e32 v69, 0x45800000, v68
	v_cndmask_b32_e64 v68, v68, v69, s[42:43]
	v_mul_f32_e32 v68, v174, v68
	v_pk_mul_f32 v[62:63], v[62:63], v[68:69] op_sel_hi:[1,0]
	v_pk_mul_f32 v[60:61], v[60:61], v[68:69] op_sel_hi:[1,0]
	v_pk_mul_f32 v[58:59], v[58:59], v[68:69] op_sel_hi:[1,0]
	v_pk_mul_f32 v[56:57], v[56:57], v[68:69] op_sel_hi:[1,0]
	s_cbranch_vccnz .LBB0_292
	ds_bpermute_b32 v76, v169, v60
	ds_bpermute_b32 v72, v169, v56
	ds_bpermute_b32 v77, v169, v61
	ds_bpermute_b32 v73, v169, v57
	ds_bpermute_b32 v74, v169, v62
	ds_bpermute_b32 v70, v169, v58
	ds_bpermute_b32 v75, v169, v63
	ds_bpermute_b32 v71, v169, v59
	s_and_saveexec_b64 s[42:43], s[36:37]
	s_cbranch_execz .LBB0_291
	v_lshl_add_u64 v[90:91], s[20:21], 0, v[64:65]
	global_load_dwordx4 v[78:81], v[90:91], off
	global_load_dwordx4 v[82:85], v[90:91], off offset:32
	global_load_dwordx4 v[86:89], v[90:91], off offset:16
	s_nop 0
	global_load_dwordx4 v[90:93], v[90:91], off offset:48
	s_waitcnt vmcnt(3)
	v_pk_mul_f32 v[62:63], v[62:63], v[80:81]
	v_pk_mul_f32 v[60:61], v[60:61], v[78:79]
	s_waitcnt vmcnt(2) lgkmcnt(5)
	v_pk_mul_f32 v[76:77], v[82:83], v[76:77]
	s_waitcnt lgkmcnt(1)
	v_pk_mul_f32 v[74:75], v[84:85], v[74:75]
	s_waitcnt vmcnt(1)
	v_pk_mul_f32 v[58:59], v[58:59], v[88:89]
	v_pk_mul_f32 v[56:57], v[56:57], v[86:87]
	s_waitcnt vmcnt(0)
	v_pk_mul_f32 v[72:73], v[90:91], v[72:73]
	s_waitcnt lgkmcnt(0)
	v_pk_mul_f32 v[70:71], v[92:93], v[70:71]
	v_pk_fma_f32 v[62:63], v[140:141], v[74:75], v[62:63]
	v_pk_fma_f32 v[60:61], v[138:139], v[76:77], v[60:61]
	v_pk_fma_f32 v[58:59], v[140:141], v[70:71], v[58:59]
	v_pk_fma_f32 v[56:57], v[138:139], v[72:73], v[56:57]

.LBB0_296:
	v_cvt_pk_bf16_f32 v52, v52, v53
	v_cvt_pk_bf16_f32 v53, v54, v55
	v_cvt_pk_bf16_f32 v55, v50, v51
	v_add_u32_e32 v50, 0x90, v148
	v_ashrrev_i32_e32 v51, 31, v50
	v_cvt_pk_bf16_f32 v54, v48, v49
	v_lshlrev_b64 v[48:49], 6, v[50:51]
	global_store_dwordx4 v[56:57], v[52:55], off offset:256 sc1
	s_and_b64 vcc, exec, s[40:41]
	s_nop 0
	v_lshl_add_u64 v[52:53], v[142:143], 0, v[48:49]
	v_mov_b32_e32 v52, v238
	v_mov_b32_e32 v53, v239
	v_mov_b32_e32 v54, v240
	v_mov_b32_e32 v55, v241
	v_mov_b32_e32 v56, v53
	v_mov_b32_e32 v57, v54
	v_mov_b32_e32 v53, v55
	v_pk_add_f32 v[52:53], v[56:57], v[52:53]
	s_nop 0
	v_add_f32_e32 v52, v52, v53
	ds_bpermute_b32 v53, v169, v52
	s_waitcnt lgkmcnt(0)
	v_add_f32_e32 v52, v52, v53
	ds_bpermute_b32 v53, v172, v52
	s_waitcnt lgkmcnt(0)
	v_add_f32_e32 v52, v52, v53
	v_fmamk_f32 v52, v52, 0x3a800000, v216
	v_mul_f32_e32 v53, 0x4b800000, v52
	v_cmp_gt_f32_e64 s[42:43], s29, v52
	s_nop 1
	v_cndmask_b32_e64 v52, v52, v53, s[42:43]
	v_rsq_f32_e32 v52, v52
	s_nop 0
	v_mul_f32_e32 v53, 0x45800000, v52
	v_cndmask_b32_e64 v52, v52, v53, s[42:43]
	v_mul_f32_e32 v52, v174, v52
	v_pk_mul_f32 v[46:47], v[46:47], v[52:53] op_sel_hi:[1,0]
	v_pk_mul_f32 v[44:45], v[44:45], v[52:53] op_sel_hi:[1,0]
	v_pk_mul_f32 v[42:43], v[42:43], v[52:53] op_sel_hi:[1,0]
	v_pk_mul_f32 v[40:41], v[40:41], v[52:53] op_sel_hi:[1,0]
	s_cbranch_vccnz .LBB0_300
	ds_bpermute_b32 v60, v169, v44
	ds_bpermute_b32 v56, v169, v40
	ds_bpermute_b32 v61, v169, v45
	ds_bpermute_b32 v57, v169, v41
	ds_bpermute_b32 v58, v169, v46
	ds_bpermute_b32 v54, v169, v42
	ds_bpermute_b32 v59, v169, v47
	ds_bpermute_b32 v55, v169, v43
	s_and_saveexec_b64 s[42:43], s[36:37]
	s_cbranch_execz .LBB0_299
	v_lshl_add_u64 v[74:75], s[20:21], 0, v[48:49]
	global_load_dwordx4 v[62:65], v[74:75], off
	global_load_dwordx4 v[66:69], v[74:75], off offset:32
	global_load_dwordx4 v[70:73], v[74:75], off offset:16
	s_nop 0
	global_load_dwordx4 v[74:77], v[74:75], off offset:48
	s_waitcnt vmcnt(3)
	v_pk_mul_f32 v[46:47], v[46:47], v[64:65]
	v_pk_mul_f32 v[44:45], v[44:45], v[62:63]
	s_waitcnt vmcnt(2) lgkmcnt(5)
	v_pk_mul_f32 v[60:61], v[66:67], v[60:61]
	s_waitcnt lgkmcnt(1)
	v_pk_mul_f32 v[58:59], v[68:69], v[58:59]
	s_waitcnt vmcnt(1)
	v_pk_mul_f32 v[42:43], v[42:43], v[72:73]
	v_pk_mul_f32 v[40:41], v[40:41], v[70:71]
	s_waitcnt vmcnt(0)
	v_pk_mul_f32 v[56:57], v[74:75], v[56:57]
	s_waitcnt lgkmcnt(0)
	v_pk_mul_f32 v[54:55], v[76:77], v[54:55]
	v_pk_fma_f32 v[46:47], v[140:141], v[58:59], v[46:47]
	v_pk_fma_f32 v[44:45], v[138:139], v[60:61], v[44:45]
	v_pk_fma_f32 v[42:43], v[140:141], v[54:55], v[42:43]
	v_pk_fma_f32 v[40:41], v[138:139], v[56:57], v[40:41]

.LBB0_304:
	v_cvt_pk_bf16_f32 v36, v36, v37
	v_cvt_pk_bf16_f32 v37, v38, v39
	v_cvt_pk_bf16_f32 v39, v34, v35
	v_add_u32_e32 v34, 0xa0, v148
	v_ashrrev_i32_e32 v35, 31, v34
	v_cvt_pk_bf16_f32 v38, v32, v33
	v_lshlrev_b64 v[32:33], 6, v[34:35]
	global_store_dwordx4 v[40:41], v[36:39], off offset:256 sc1
	s_and_b64 vcc, exec, s[40:41]
	s_nop 0
	v_lshl_add_u64 v[36:37], v[142:143], 0, v[32:33]
	v_mov_b32_e32 v36, v222
	v_mov_b32_e32 v37, v223
	v_mov_b32_e32 v38, v224
	v_mov_b32_e32 v39, v225
	v_mov_b32_e32 v40, v37
	v_mov_b32_e32 v41, v38
	v_mov_b32_e32 v37, v39
	v_pk_add_f32 v[36:37], v[40:41], v[36:37]
	s_nop 0
	v_add_f32_e32 v36, v36, v37
	ds_bpermute_b32 v37, v169, v36
	s_waitcnt lgkmcnt(0)
	v_add_f32_e32 v36, v36, v37
	ds_bpermute_b32 v37, v172, v36
	s_waitcnt lgkmcnt(0)
	v_add_f32_e32 v36, v36, v37
	v_fmamk_f32 v36, v36, 0x3a800000, v216
	v_mul_f32_e32 v37, 0x4b800000, v36
	v_cmp_gt_f32_e64 s[42:43], s29, v36
	s_nop 1
	v_cndmask_b32_e64 v36, v36, v37, s[42:43]
	v_rsq_f32_e32 v36, v36
	s_nop 0
	v_mul_f32_e32 v37, 0x45800000, v36
	v_cndmask_b32_e64 v36, v36, v37, s[42:43]
	v_mul_f32_e32 v36, v174, v36
	v_pk_mul_f32 v[30:31], v[30:31], v[36:37] op_sel_hi:[1,0]
	v_pk_mul_f32 v[28:29], v[28:29], v[36:37] op_sel_hi:[1,0]
	v_pk_mul_f32 v[26:27], v[26:27], v[36:37] op_sel_hi:[1,0]
	v_pk_mul_f32 v[24:25], v[24:25], v[36:37] op_sel_hi:[1,0]
	s_cbranch_vccnz .LBB0_308
	ds_bpermute_b32 v44, v169, v28
	ds_bpermute_b32 v40, v169, v24
	ds_bpermute_b32 v45, v169, v29
	ds_bpermute_b32 v41, v169, v25
	ds_bpermute_b32 v42, v169, v30
	ds_bpermute_b32 v38, v169, v26
	ds_bpermute_b32 v43, v169, v31
	ds_bpermute_b32 v39, v169, v27
	s_and_saveexec_b64 s[42:43], s[36:37]
	s_cbranch_execz .LBB0_307
	v_lshl_add_u64 v[58:59], s[20:21], 0, v[32:33]
	global_load_dwordx4 v[46:49], v[58:59], off
	global_load_dwordx4 v[50:53], v[58:59], off offset:32
	global_load_dwordx4 v[54:57], v[58:59], off offset:16
	s_nop 0
	global_load_dwordx4 v[58:61], v[58:59], off offset:48
	s_waitcnt vmcnt(3)
	v_pk_mul_f32 v[30:31], v[30:31], v[48:49]
	v_pk_mul_f32 v[28:29], v[28:29], v[46:47]
	s_waitcnt vmcnt(2) lgkmcnt(5)
	v_pk_mul_f32 v[44:45], v[50:51], v[44:45]
	s_waitcnt lgkmcnt(1)
	v_pk_mul_f32 v[42:43], v[52:53], v[42:43]
	s_waitcnt vmcnt(1)
	v_pk_mul_f32 v[26:27], v[26:27], v[56:57]
	v_pk_mul_f32 v[24:25], v[24:25], v[54:55]
	s_waitcnt vmcnt(0)
	v_pk_mul_f32 v[40:41], v[58:59], v[40:41]
	s_waitcnt lgkmcnt(0)
	v_pk_mul_f32 v[38:39], v[60:61], v[38:39]
	v_pk_fma_f32 v[30:31], v[140:141], v[42:43], v[30:31]
	v_pk_fma_f32 v[28:29], v[138:139], v[44:45], v[28:29]
	v_pk_fma_f32 v[26:27], v[140:141], v[38:39], v[26:27]
	v_pk_fma_f32 v[24:25], v[138:139], v[40:41], v[24:25]

.LBB0_312:
	v_cvt_pk_bf16_f32 v20, v20, v21
	v_cvt_pk_bf16_f32 v21, v22, v23
	v_cvt_pk_bf16_f32 v23, v18, v19
	v_add_u32_e32 v18, 0xb0, v148
	v_ashrrev_i32_e32 v19, 31, v18
	v_cvt_pk_bf16_f32 v22, v16, v17
	v_lshlrev_b64 v[16:17], 6, v[18:19]
	global_store_dwordx4 v[24:25], v[20:23], off offset:256 sc1
	s_and_b64 vcc, exec, s[40:41]
	s_nop 0
	v_lshl_add_u64 v[20:21], v[142:143], 0, v[16:17]
	v_mov_b32_e32 v20, v208
	v_mov_b32_e32 v21, v209
	v_mov_b32_e32 v22, v210
	v_mov_b32_e32 v23, v211
	v_mov_b32_e32 v24, v21
	v_mov_b32_e32 v25, v22
	v_mov_b32_e32 v21, v23
	v_pk_add_f32 v[20:21], v[24:25], v[20:21]
	s_nop 0
	v_add_f32_e32 v20, v20, v21
	ds_bpermute_b32 v21, v169, v20
	s_waitcnt lgkmcnt(0)
	v_add_f32_e32 v20, v20, v21
	ds_bpermute_b32 v21, v172, v20
	s_waitcnt lgkmcnt(0)
	v_add_f32_e32 v20, v20, v21
	v_fmamk_f32 v20, v20, 0x3a800000, v216
	v_mul_f32_e32 v21, 0x4b800000, v20
	v_cmp_gt_f32_e64 s[42:43], s29, v20
	s_nop 1
	v_cndmask_b32_e64 v20, v20, v21, s[42:43]
	v_rsq_f32_e32 v20, v20
	s_nop 0
	v_mul_f32_e32 v21, 0x45800000, v20
	v_cndmask_b32_e64 v20, v20, v21, s[42:43]
	v_mul_f32_e32 v20, v174, v20
	v_pk_mul_f32 v[14:15], v[14:15], v[20:21] op_sel_hi:[1,0]
	v_pk_mul_f32 v[12:13], v[12:13], v[20:21] op_sel_hi:[1,0]
	v_pk_mul_f32 v[10:11], v[10:11], v[20:21] op_sel_hi:[1,0]
	v_pk_mul_f32 v[8:9], v[8:9], v[20:21] op_sel_hi:[1,0]
	s_cbranch_vccnz .LBB0_316
	ds_bpermute_b32 v28, v169, v12
	ds_bpermute_b32 v24, v169, v8
	ds_bpermute_b32 v29, v169, v13
	ds_bpermute_b32 v25, v169, v9
	ds_bpermute_b32 v26, v169, v14
	ds_bpermute_b32 v22, v169, v10
	ds_bpermute_b32 v27, v169, v15
	ds_bpermute_b32 v23, v169, v11
	s_and_saveexec_b64 s[42:43], s[36:37]
	s_cbranch_execz .LBB0_315
	v_lshl_add_u64 v[42:43], s[20:21], 0, v[16:17]
	global_load_dwordx4 v[30:33], v[42:43], off
	global_load_dwordx4 v[34:37], v[42:43], off offset:32
	global_load_dwordx4 v[38:41], v[42:43], off offset:16
	s_nop 0
	global_load_dwordx4 v[42:45], v[42:43], off offset:48
	s_waitcnt vmcnt(3)
	v_pk_mul_f32 v[14:15], v[14:15], v[32:33]
	v_pk_mul_f32 v[12:13], v[12:13], v[30:31]
	s_waitcnt vmcnt(2) lgkmcnt(5)
	v_pk_mul_f32 v[28:29], v[34:35], v[28:29]
	s_waitcnt lgkmcnt(1)
	v_pk_mul_f32 v[26:27], v[36:37], v[26:27]
	s_waitcnt vmcnt(1)
	v_pk_mul_f32 v[10:11], v[10:11], v[40:41]
	v_pk_mul_f32 v[8:9], v[8:9], v[38:39]
	s_waitcnt vmcnt(0)
	v_pk_mul_f32 v[24:25], v[42:43], v[24:25]
	s_waitcnt lgkmcnt(0)
	v_pk_mul_f32 v[22:23], v[44:45], v[22:23]
	v_pk_fma_f32 v[14:15], v[140:141], v[26:27], v[14:15]
	v_pk_fma_f32 v[12:13], v[138:139], v[28:29], v[12:13]
	v_pk_fma_f32 v[10:11], v[140:141], v[22:23], v[10:11]
	v_pk_fma_f32 v[8:9], v[138:139], v[24:25], v[8:9]
